# v49 plus P0 publish of the modulation columns by write-through (sc1) stores + counter, no L2 write-back by the 64 producer workgroups
# speedup vs baseline: 1.0156x; 1.0156x over previous
.LBB0_44:
	v_add_u32_e32 v5, s0, v4
	ds_read2_b32 v[6:7], v5 offset1:160
	v_add_u32_e32 v8, 0x400, v5
	v_add_u32_e32 v10, 0xa00, v5
	v_add_u32_e32 v12, 0xe00, v5
	v_add_u32_e32 v14, 0x1400, v5
	s_waitcnt vmcnt(0) lgkmcnt(0)
	v_add_f32_e32 v3, v3, v6
	v_add_u32_e32 v16, 0x1800, v5
	v_add_u32_e32 v18, 0x1e00, v5
	v_add_f32_e32 v3, v3, v7
	v_add_u32_e32 v5, 0x2200, v5
	ds_read2_b32 v[8:9], v8 offset0:64 offset1:224
	ds_read2_b32 v[10:11], v10 offset1:160
	ds_read2_b32 v[12:13], v12 offset0:64 offset1:224
	ds_read2_b32 v[14:15], v14 offset1:160
	ds_read2_b32 v[16:17], v16 offset0:64 offset1:224
	ds_read2_b32 v[18:19], v18 offset1:160
	ds_read2_b32 v[20:21], v5 offset0:64 offset1:224
	s_waitcnt lgkmcnt(6)
	v_add_f32_e32 v3, v3, v8
	v_add_f32_e32 v3, v3, v9
	s_waitcnt lgkmcnt(5)
	v_add_f32_e32 v3, v3, v10
	v_add_f32_e32 v3, v3, v11
	s_waitcnt lgkmcnt(4)
	v_add_f32_e32 v3, v3, v12
	v_add_f32_e32 v3, v3, v13
	s_waitcnt lgkmcnt(3)
	v_add_f32_e32 v3, v3, v14
	v_add_f32_e32 v3, v3, v15
	s_waitcnt lgkmcnt(2)
	v_add_f32_e32 v3, v3, v16
	v_add_f32_e32 v3, v3, v17
	s_waitcnt lgkmcnt(1)
	v_add_f32_e32 v3, v3, v18
	v_add_f32_e32 v3, v3, v19
	s_addk_i32 s0, 0x2800
	s_waitcnt lgkmcnt(0)
	v_add_f32_e32 v3, v3, v20
	s_cmpk_eq_u32 s0, 0xf000
	v_add_f32_e32 v3, v3, v21
	s_cbranch_scc0 .LBB0_44
	s_movk_i32 s0, 0x1800
	v_mov_b32_e32 v4, s4
	v_mad_u32_u24 v2, v2, s0, v4
	v_or_b32_e32 v4, v2, v1
	v_readlane_b32 s0, v242, 34
	v_ashrrev_i32_e32 v5, 31, v4
	v_readlane_b32 s1, v242, 35
	s_nop 1
	v_lshl_add_u64 v[4:5], v[4:5], 2, s[0:1]
	global_store_dword v[4:5], v3, off sc1
.LBB0_46:
	s_or_b64 exec, exec, s[6:7]
	s_cmp_gt_i32 s38, 63
	s_barrier
	s_cbranch_scc1 .LBB0_51
	s_waitcnt vmcnt(0)
	s_barrier
	s_and_saveexec_b64 s[4:5], s[14:15]
	s_cbranch_execz .LBB0_50
	s_mov_b64 s[6:7], exec
	v_mbcnt_lo_u32_b32 v1, s6, 0
	s_waitcnt vmcnt(0)
	s_waitcnt vmcnt(0)
	v_mbcnt_hi_u32_b32 v1, s7, v1
	v_cmp_eq_u32_e32 vcc, 0, v1
	s_and_b64 s[0:1], exec, vcc
	s_mov_b64 exec, s[0:1]
	s_cbranch_execz .LBB0_50
	s_bcnt1_i32_b64 s0, s[6:7]
	v_mov_b32_e32 v1, 0
	v_mov_b32_e32 v2, s0
	global_atomic_add v1, v2, s[8:9]
